# next-unit L2 warm-up: MLA tail touches the next unit's Q rows, NA compute start touches the next unit's K/V rows (dummy dword loads, counted waits adjusted)
# baseline (speedup 1.0000x reference)
.LBB0_1380:
	s_add_i32 s98, s37, 1
	s_lshl_b32 s98, s98, 3
	s_or_b32 s98, s98, s3
	s_mul_i32 s98, s98, s21
	s_add_i32 s98, s98, s20
	s_cmpk_gt_i32 s98, 0x3ff
	s_cbranch_scc1 .Lmla_nowarm
	s_bfe_u32 s99, s98, 0x30003
	s_mul_i32 s99, s99, 0xc0
	s_ashr_i32 s100, s98, 6
	s_lshl_b32 s100, s100, 11
	s_lshl_b32 s98, s98, 8
	s_and_b32 s98, s98, 0x700
	s_or_b32 s98, s100, s98
	v_lshrrev_b32_e32 v236, 1, v162
	v_add_u32_e32 v236, s98, v236
	v_and_b32_e32 v238, 1, v162
	v_lshlrev_b32_e32 v238, 7, v238
	v_add_u32_e32 v238, s99, v238
	v_mov_b32_e32 v239, 0
	v_mad_i64_i32 v[236:237], s[100:101], v236, s29, v[238:239]
	v_lshl_add_u64 v[236:237], s[18:19], 0, v[236:237]
	global_load_dword v240, v[236:237], off

.LBB0_1387:
	s_or_b64 exec, exec, s[4:5]
	v_lshrrev_b32_e32 v14, 2, v2
	v_ashrrev_i32_e32 v17, 8, v2
	v_and_b32_e32 v20, 48, v14
	v_add_u32_e32 v19, s6, v17
	v_sub_u32_e64 v14, v20, 8 clamp
	v_min_u32_e32 v140, 32, v14
	v_lshlrev_b32_e32 v14, 6, v19
	s_and_b32 s36, s34, 30
	v_and_b32_e32 v139, 15, v2
	v_ashrrev_i32_e32 v15, 31, v14
	v_sub_u32_e64 v0, s36, 4 clamp
	v_lshl_add_u64 v[14:15], s[0:1], 0, v[14:15]
	v_or_b32_e32 v20, v20, v139
	v_min_u32_e32 v0, 24, v0
	v_or_b32_e32 v14, v20, v14
	s_lshl_b32 s4, s7, 6
	v_lshlrev_b32_e32 v13, 13, v0
	v_max_i32_e32 v0, 4, v19
	v_lshlrev_b64 v[118:119], 9, v[14:15]
	v_lshlrev_b64 v[14:15], 10, v[14:15]
	v_add_u32_e32 v0, -4, v0
	v_bfe_u32 v98, v2, 4, 2
	v_lshl_add_u64 v[14:15], s[64:65], 0, v[14:15]
	s_lshl_b32 s26, s4, 1
	v_min_u32_e32 v21, 24, v0
	v_lshl_add_u64 v[14:15], v[14:15], 0, s[26:27]
	v_lshlrev_b32_e32 v0, 4, v98
	v_lshl_add_u64 v[14:15], v[14:15], 0, v[0:1]
	v_sub_u32_e64 v14, v20, 8 clamp
	v_lshlrev_b32_e32 v141, 2, v98
	v_min_u32_e32 v14, 48, v14
	v_add_u32_e32 v15, v140, v141
	v_add_u32_e32 v66, 16, v14
	v_sub_u32_e32 v67, v15, v20
	v_cmp_ge_u32_e32 vcc, v15, v14
	v_cmp_lt_u32_e64 s[0:1], v15, v66
	v_med3_i32 v142, v67, -15, 15
	v_or_b32_e32 v67, 1, v15
	s_and_b64 s[4:5], vcc, s[0:1]
	v_cmp_ge_u32_e32 vcc, v67, v14
	v_cmp_lt_u32_e64 s[0:1], v67, v66
	v_sub_u32_e32 v67, v67, v20
	v_med3_i32 v143, v67, -15, 15
	v_or_b32_e32 v67, 2, v15
	s_and_b64 s[6:7], vcc, s[0:1]
	v_cmp_ge_u32_e32 vcc, v67, v14
	v_cmp_lt_u32_e64 s[0:1], v67, v66
	v_sub_u32_e32 v67, v67, v20
	v_med3_i32 v144, v67, -15, 15
	v_or_b32_e32 v67, 3, v15
	s_and_b64 s[8:9], vcc, s[0:1]
	v_cmp_ge_u32_e32 vcc, v67, v14
	v_cmp_lt_u32_e64 s[0:1], v67, v66
	v_sub_u32_e32 v67, v67, v20
	v_med3_i32 v145, v67, -15, 15
	v_add_u32_e32 v67, 16, v15
	s_and_b64 s[10:11], vcc, s[0:1]
	v_cmp_ge_u32_e32 vcc, v67, v14
	v_sub_u32_e32 v67, v67, v20
	v_cmp_lt_u32_e64 s[0:1], v15, v14
	v_med3_i32 v146, v67, -15, 15
	v_add_u32_e32 v67, 17, v15
	s_and_b64 s[12:13], vcc, s[0:1]
	v_cmp_ge_u32_e32 vcc, v67, v14
	v_cmp_lt_u32_e64 s[0:1], v67, v66
	v_sub_u32_e32 v67, v67, v20
	v_med3_i32 v147, v67, -15, 15
	v_add_u32_e32 v67, 18, v15
	s_and_b64 s[14:15], vcc, s[0:1]
	v_cmp_ge_u32_e32 vcc, v67, v14
	v_cmp_lt_u32_e64 s[0:1], v67, v66
	v_add_u32_e32 v15, 19, v15
	s_and_b64 s[16:17], vcc, s[0:1]
	v_cmp_ge_u32_e32 vcc, v15, v14
	v_cmp_lt_u32_e64 s[0:1], v15, v66
	v_or_b32_e32 v120, 0x1d400, v0
	v_sub_u32_e32 v67, v67, v20
	s_and_b64 s[18:19], vcc, s[0:1]
	v_mad_u32_u24 v0, v139, s42, v120
	v_cmp_lt_i32_e32 vcc, v135, v136
	v_med3_i32 v148, v67, -15, 15
	s_waitcnt lgkmcnt(0)
	s_barrier
	s_add_i32 s98, s48, 1
	s_lshl_b32 s98, s98, 3
	s_or_b32 s98, s98, s3
	s_mul_i32 s98, s98, s21
	s_add_i32 s98, s98, s20
	s_min_i32 s98, s98, 0x7ff
	s_bfe_u32 s99, s98, 0x30004
	s_lshl_b32 s99, s99, 7
	s_and_b32 s100, s98, 15
	s_lshl_b32 s100, s100, 1
	s_sub_i32 s100, s100, 4
	s_max_i32 s100, s100, 0
	s_min_i32 s100, s100, 24
	s_lshl_b32 s100, s100, 6
	s_ashr_i32 s101, s98, 7
	s_lshl_b32 s98, s101, 11
	s_add_i32 s100, s100, s98
	s_lshl_b32 s101, s101, 8
	s_add_i32 s101, s101, 0x8000
	v_cmp_gt_u32_e32 vcc, 0x100, v162
	v_mov_b32_e32 v238, 0x4400000
	v_mov_b32_e32 v239, 0x2000000
	s_nop 0
	v_cndmask_b32_e32 v238, v239, v238, vcc
	v_add_u32_e32 v238, s99, v238
	v_and_b32_e32 v236, 0xff, v162
	v_and_b32_e32 v237, 63, v162
	v_add_u32_e32 v240, s101, v236
	v_lshl_add_u32 v240, v240, 10, v238
	v_mov_b32_e32 v241, 0
	v_add_u32_e32 v242, s100, v236
	v_lshl_add_u32 v242, v242, 10, v238
	v_mov_b32_e32 v243, 0
	v_add_u32_e32 v244, 0x40000, v242
	v_mov_b32_e32 v245, 0
	v_add_u32_e32 v237, s100, v237
	v_add_u32_e32 v237, 0x200, v237
	v_lshl_add_u32 v236, v237, 10, v238
	v_mov_b32_e32 v237, 0
	v_lshl_add_u64 v[240:241], s[64:65], 0, v[240:241]
	v_lshl_add_u64 v[242:243], s[64:65], 0, v[242:243]
	v_lshl_add_u64 v[244:245], s[64:65], 0, v[244:245]
	v_lshl_add_u64 v[236:237], s[64:65], 0, v[236:237]
	global_load_dword v215, v[240:241], off
	global_load_dword v216, v[242:243], off
	global_load_dword v217, v[244:245], off
	global_load_dword v218, v[236:237], off
	ds_read_b128 v[66:69], v0
	ds_read_b128 v[70:73], v0 offset:64
	ds_read_b128 v[74:77], v0 offset:2304
	ds_read_b128 v[78:81], v0 offset:2368
	ds_read_b128 v[82:85], v0 offset:4608
	ds_read_b128 v[86:89], v0 offset:4672
	ds_read_b128 v[90:93], v0 offset:6912
	ds_read_b128 v[94:97], v0 offset:6976
	v_cndmask_b32_e32 v0, v134, v135, vcc
	v_cmp_lt_i32_e32 vcc, v137, v136
	v_lshlrev_b32_e32 v150, 2, v0
	v_sub_u32_e32 v153, v21, v7
	v_cndmask_b32_e32 v0, v134, v137, vcc
	v_lshlrev_b32_e32 v151, 2, v0
	v_bfe_u32 v0, v2, 2, 2
	v_or_b32_e32 v0, v141, v0
	v_mul_u32_u24_e32 v152, 0x90, v0
	v_lshlrev_b32_e32 v0, 2, v2
	v_sub_u32_e32 v14, v15, v20
	v_and_b32_e32 v20, 12, v0
	v_lshl_or_b32 v0, v153, 6, v140
	v_add_lshl_u32 v0, v0, v139, 7
	v_add_u32_e32 v154, 0x14400, v0
	v_add_u32_e32 v157, 0x14c00, v0
	v_add_u32_e32 v158, 0x16400, v0
	v_add_u32_e32 v159, 0x16c00, v0
	v_xor_b32_e32 v0, v3, v2
	v_lshlrev_b32_e32 v0, 4, v0
	v_and_b32_e32 v0, 0x70, v0
	v_lshl_or_b32 v0, v3, 7, v0
	v_add_u32_e32 v161, 0x14400, v0
	v_xor_b32_e32 v0, v4, v2
	v_lshlrev_b32_e32 v0, 4, v0
	v_and_b32_e32 v0, 0x70, v0
	v_lshl_or_b32 v0, v4, 7, v0
	v_add_u32_e32 v164, 0x14400, v0
	v_xor_b32_e32 v0, v5, v2
	v_lshlrev_b32_e32 v0, 4, v0
	v_and_b32_e32 v0, 0x70, v0
	v_lshl_or_b32 v0, v5, 7, v0
	v_add_u32_e32 v165, 0x14400, v0
	v_xor_b32_e32 v0, v6, v2
	v_lshlrev_b32_e32 v0, 4, v0
	v_and_b32_e32 v0, 0x70, v0
	v_lshl_or_b32 v0, v6, 7, v0
	v_add_u32_e32 v166, 0x14400, v0
	v_xor_b32_e32 v0, v12, v2
	v_lshlrev_b32_e32 v0, 4, v0
	v_and_b32_e32 v0, 0x70, v0
	v_lshl_or_b32 v0, v12, 7, v0
	v_add_u32_e32 v167, 0x14400, v0
	v_xor_b32_e32 v0, v11, v2
	v_lshlrev_b32_e32 v0, 4, v0
	v_and_b32_e32 v0, 0x70, v0
	v_lshl_or_b32 v0, v11, 7, v0
	v_add_u32_e32 v168, 0x14400, v0
	v_xor_b32_e32 v0, v10, v2
	v_lshlrev_b32_e32 v0, 4, v0
	v_and_b32_e32 v0, 0x70, v0
	v_lshl_or_b32 v0, v10, 7, v0
	v_add_u32_e32 v169, 0x14400, v0
	v_xor_b32_e32 v0, v9, v2
	v_lshlrev_b32_e32 v0, 4, v0
	v_and_b32_e32 v0, 0x70, v0
	v_lshl_or_b32 v0, v9, 7, v0
	v_add_u32_e32 v170, 0x14400, v0
	v_xor_b32_e32 v0, v8, v2
	v_lshlrev_b32_e32 v0, 4, v0
	v_and_b32_e32 v0, 0x70, v0
	v_lshl_or_b32 v0, v8, 7, v0
	v_add_u32_e32 v171, 0x14400, v0
	v_add_u32_e32 v0, s36, v17
	v_max_i32_e32 v0, 4, v0
	v_lshrrev_b32_e32 v16, 4, v2
	v_and_b32_e32 v7, 7, v2
	v_add_u32_e32 v0, -4, v0
	v_med3_i32 v149, v14, -15, 15
	v_bitop3_b32 v14, v16, v7, 3 bitop3:0x6c
	v_bitop3_b32 v7, v98, v7, 4 bitop3:0x36
	v_min_u32_e32 v0, 24, v0
	v_add_lshl_u32 v2, v140, v139, 7
	v_lshlrev_b32_e32 v155, 4, v14
	v_lshlrev_b32_e32 v156, 4, v7
	v_lshl_add_u32 v0, v0, 13, v2
	v_or_b32_e32 v2, v0, v156
	v_or_b32_e32 v0, v0, v155
	v_sub_u32_e32 v173, v2, v13
	v_sub_u32_e32 v174, v0, v13
	v_mov_b32_e32 v2, v1
	v_mov_b32_e32 v3, v1
	v_mov_b32_e32 v4, v1
	v_mov_b32_e32 v5, v1
	v_mov_b32_e32 v6, v1
	v_mov_b32_e32 v7, v1
	v_mov_b32_e32 v8, v1
	v_mov_b32_e32 v9, v1
	v_mov_b32_e32 v10, v1
	v_mov_b32_e32 v11, v1
	v_mov_b32_e32 v12, v1
	v_mov_b32_e32 v13, v1
	v_mov_b32_e32 v14, v1
	v_mov_b32_e32 v15, v1
	v_mov_b32_e32 v0, v1
	v_mov_b64_e32 v[16:17], v[14:15]
	s_mov_b32 s28, 0
	v_sub_u32_e32 v160, v21, v19
	v_or_b32_e32 v172, 64, v140
	v_mov_b32_e32 v98, v1
	v_mov_b32_e32 v99, v1
	v_mov_b32_e32 v100, v1
	v_mov_b32_e32 v101, v1
	v_mov_b32_e32 v175, 0
	s_mov_b32 s49, 0x15600
	v_lshlrev_b32_e32 v176, 1, v20
	s_mov_b32 s50, 0
	v_mov_b64_e32 v[14:15], v[12:13]
	v_mov_b64_e32 v[12:13], v[10:11]
	v_mov_b64_e32 v[10:11], v[8:9]
	v_mov_b64_e32 v[8:9], v[6:7]
	v_mov_b64_e32 v[6:7], v[4:5]
	v_mov_b64_e32 v[4:5], v[2:3]
	v_mov_b64_e32 v[2:3], v[0:1]
	s_branch .LBB0_1389

.LBB0_1391:
	v_xor_b32_e32 v106, 0x80000000, v175
	v_mov_b32_e32 v107, v106
	v_mov_b32_e32 v108, v106
	v_mov_b32_e32 v109, v106
	s_and_b32 s51, s50, 3
	s_cmp_eq_u32 s51, 3
	s_waitcnt vmcnt(5) lgkmcnt(7)
	v_mfma_f32_16x16x32_bf16 v[102:105], v[66:69], v[58:61], v[106:109]
	s_waitcnt vmcnt(4) lgkmcnt(6)
	v_mfma_f32_16x16x32_bf16 v[110:113], v[70:73], v[62:65], v[102:105]
	s_waitcnt lgkmcnt(5)
	v_mfma_f32_16x16x32_bf16 v[102:105], v[74:77], v[58:61], v[106:109]
	s_waitcnt lgkmcnt(4)
	v_mfma_f32_16x16x32_bf16 v[114:117], v[78:81], v[62:65], v[102:105]
	s_waitcnt lgkmcnt(3)
	v_mfma_f32_16x16x32_bf16 v[102:105], v[82:85], v[58:61], v[106:109]
	s_waitcnt lgkmcnt(1)
	v_mfma_f32_16x16x32_bf16 v[106:109], v[90:93], v[58:61], v[106:109]
	v_mfma_f32_16x16x32_bf16 v[102:105], v[86:89], v[62:65], v[102:105]
	s_waitcnt lgkmcnt(0)
	v_mfma_f32_16x16x32_bf16 v[106:109], v[94:97], v[62:65], v[106:109]
	s_cbranch_scc1 .LBB0_1397
	s_cmp_gt_u32 s50, 2
	s_mov_b64 s[0:1], -1
	s_cbranch_scc0 .LBB0_1394
	v_add_u32_e32 v21, s28, v174
	v_add_u32_e32 v70, s28, v173
	v_add_u32_e32 v20, 0x8400, v21
	v_add_u32_e32 v0, 0x8400, v70
	v_add_u32_e32 v19, 0x8c00, v21
	v_add_u32_e32 v66, 0x8c00, v70
	v_add_u32_e32 v67, 0xa400, v21
	v_add_u32_e32 v68, 0xa400, v70
	v_add_u32_e32 v69, 0xac00, v21
	v_add_u32_e32 v21, 0xac00, v70
	s_mov_b64 s[0:1], 0
